# v020 with the GQA row-sum accumulation done by 16 packed v_pk_add_f32 per tile (pair v112/v113, v113 re-zeroed at exit) instead of 32 scalar adds; f32 throughout
# baseline (speedup 1.0000x reference)
; #define SBAR() __builtin_amdgcn_sched_barrier(0)
; #define NAM(P0, P1, t) do { if constexpr (NA) na_mask(P0, P1, kr_lo + (t), r0, qrow, qc, c0, hi, bl); } while (0)
; #define PSM(P0, P1, MN, AL) do { if constexpr (NA) partialSM(P0, P1, m_reg, MN, AL); else { AL = 1.f; _Pragma("unroll") for (int r = 0; r < 16; ++r) P0[r] = __builtin_amdgcn_exp2f(P0[r]); } } while (0)
; #define RESCN(a) do { if constexpr (NA) RESC(a); } while (0)
; #define VM0() asm volatile("s_waitcnt vmcnt(0)" ::: "memory")
; #define NAM(P0, P1, t) do { if constexpr (NA) na_mask(P0, P1, kr_lo + (t), r0, qrow, qc, c0, hi, bl); } while (0)
; #define RESCN(a) do { if constexpr (NA) RESC(a); } while (0)
; __device__ __forceinline__ void finishSM(f32x16& p0, f32x16& p1, float alpha, float& l_reg, bf16x8& pa0, bf16x8& pa1, bf16x8& pa2, bf16x8& pa3) {
;   for (int r = 0; r < 16; ++r) p1[r] = __builtin_amdgcn_exp2f(p1[r]);
;   float ps = 0; for (int r = 0; r < 16; ++r) ps += p0[r]; for (int r = 0; r < 16; ++r) ps += p1[r];
;   { auto rr = __builtin_amdgcn_permlane32_swap(__float_as_uint(ps), __float_as_uint(ps), false, false);
;     ps = __uint_as_float(rr[0]) + __uint_as_float(rr[1]); }
;   l_reg = l_reg * alpha + ps;
;     ...
;   PK4(p0, 0, pa0); PK4(p0, 8, pa1); PK4(p1, 0, pa2); PK4(p1, 8, pa3);
; template <bool NA, int ROWB>
; __device__ __forceinline__ void attn_dma(const bf16* __restrict__ Qb, const bf16* __restrict__ Kh, const bf16* __restrict__ Vh, bf16* __restrict__ Ob, int NT, char* lds, const int tid, float* __restrict__ ssb, int qrow0, int kr_lo, const float* bl) {
;     ...
;   for (int t = 1; t + 1 < NT; t += 2) {
;     DMA_TILE(t + 1, bn);
;     SBAR(); qkt<false>(pB0, pB1, (const bf16*)(K_lds + bc * SHM_K), qr, nullptr, r32, hi); NAM(pB0, pB1, t);
;     finishSM(pA0, pA1, alA, l_reg, pa0, pa1, pa2, pa3); SBAR();
;     pv_d0(o, vb0 + bp * (int)SHM_V, pa0, pa1, pa2, pa3); PSM(pB0, pB1, mnB, alB); RESCN(alB);
;     VM0(); __syncthreads();
;     bp = bc; bc = bn; bn = NEXTB(bn);
;     if (t + 2 < NT) DMA_TILE(t + 2, bn);
;     SBAR(); qkt<false>(pA0, pA1, (const bf16*)(K_lds + bc * SHM_K), qr, nullptr, r32, hi); NAM(pA0, pA1, t + 1);
;     finishSM(pB0, pB1, alB, l_reg, pa0, pa1, pa2, pa3); SBAR();
;     pv_d0(o, vb0 + bp * (int)SHM_V, pa0, pa1, pa2, pa3); PSM(pA0, pA1, mnA, alA); RESCN(alA);
.Lgqa_lead:
	v_mov_b32_e32 v80, v212
	v_mov_b32_e32 v81, v214
	v_mov_b32_e32 v82, v210
	v_mov_b32_e32 v83, v213
	v_mov_b32_e32 v84, v208
	v_mov_b32_e32 v85, v211
	v_mov_b32_e32 v86, v207
	v_mov_b32_e32 v87, v209
	v_mov_b32_e32 v88, v203
	v_mov_b32_e32 v89, v206
	v_mov_b32_e32 v90, v198
	v_mov_b32_e32 v91, v205
	v_mov_b32_e32 v92, v196
	v_mov_b32_e32 v93, v199
	v_mov_b32_e32 v94, v175
	v_mov_b32_e32 v95, v197
	v_add_u32_e32 v215, s24, v195
	ds_read_b64_tr_b16 v[146:147], v215 offset:0
	ds_read_b64_tr_b16 v[148:149], v215 offset:2048
	ds_read_b64_tr_b16 v[150:151], v215 offset:4096
	ds_read_b64_tr_b16 v[152:153], v215 offset:6144
	ds_read_b64_tr_b16 v[154:155], v215 offset:8192
	ds_read_b64_tr_b16 v[156:157], v215 offset:10240
	ds_read_b64_tr_b16 v[158:159], v215 offset:12288
	ds_read_b64_tr_b16 v[160:161], v215 offset:14336
	ds_read_b64_tr_b16 v[176:177], v215 offset:512
	ds_read_b64_tr_b16 v[178:179], v215 offset:2560
	ds_read_b64_tr_b16 v[180:181], v215 offset:4608
	ds_read_b64_tr_b16 v[182:183], v215 offset:6656
	ds_read_b64_tr_b16 v[216:217], v215 offset:8704
	ds_read_b64_tr_b16 v[218:219], v215 offset:10752
	ds_read_b64_tr_b16 v[220:221], v215 offset:12800
	ds_read_b64_tr_b16 v[222:223], v215 offset:14848
	ds_read_b64_tr_b16 v[224:225], v215 offset:1024
	ds_read_b64_tr_b16 v[226:227], v215 offset:3072
	ds_read_b64_tr_b16 v[234:235], v215 offset:5120
	ds_read_b64_tr_b16 v[236:237], v215 offset:7168
	ds_read_b64_tr_b16 v[240:241], v215 offset:9216
	ds_read_b64_tr_b16 v[242:243], v215 offset:11264
	ds_read_b64_tr_b16 v[244:245], v215 offset:13312
	ds_read_b64_tr_b16 v[246:247], v215 offset:15360
	ds_read_b64_tr_b16 v[248:249], v215 offset:1536
	ds_read_b64_tr_b16 v[250:251], v215 offset:3584
	ds_read_b64_tr_b16 v[196:197], v215 offset:5632
	ds_read_b64_tr_b16 v[198:199], v215 offset:7680
	ds_read_b64_tr_b16 v[206:207], v215 offset:9728
	ds_read_b64_tr_b16 v[208:209], v215 offset:11776
	ds_read_b64_tr_b16 v[210:211], v215 offset:13824
	ds_read_b64_tr_b16 v[212:213], v215 offset:15872
	v_add_u32_e32 v229, s0, v187
	v_add_u32_e32 v230, s0, v188
	v_add_u32_e32 v232, s0, v189
	v_add_u32_e32 v238, s0, v190
	v_add_u32_e32 v203, s0, v191
	v_add_u32_e32 v205, s0, v192
	v_add_u32_e32 v214, s0, v193
	v_add_u32_e32 v175, s0, v194
	v_exp_f32_e32 v64, v64
	v_exp_f32_e32 v65, v65
	v_exp_f32_e32 v66, v66
	v_exp_f32_e32 v67, v67
	v_exp_f32_e32 v68, v68
	v_exp_f32_e32 v69, v69
	v_exp_f32_e32 v70, v70
	v_exp_f32_e32 v71, v71
	v_exp_f32_e32 v72, v72
	v_exp_f32_e32 v73, v73
	v_exp_f32_e32 v74, v74
	v_exp_f32_e32 v75, v75
	v_exp_f32_e32 v76, v76
	v_exp_f32_e32 v77, v77
	v_exp_f32_e32 v78, v78
	v_exp_f32_e32 v79, v79
	v_cvt_pk_bf16_f32 v96, v80, v81
	v_cvt_pk_bf16_f32 v97, v82, v83
	v_cvt_pk_bf16_f32 v98, v84, v85
	v_cvt_pk_bf16_f32 v99, v86, v87
	v_cvt_pk_bf16_f32 v100, v88, v89
	v_cvt_pk_bf16_f32 v101, v90, v91
	v_cvt_pk_bf16_f32 v102, v92, v93
	v_cvt_pk_bf16_f32 v103, v94, v95
	v_cvt_pk_bf16_f32 v104, v64, v65
	v_cvt_pk_bf16_f32 v105, v66, v67
	v_cvt_pk_bf16_f32 v106, v68, v69
	v_cvt_pk_bf16_f32 v107, v70, v71
	v_cvt_pk_bf16_f32 v108, v72, v73
	v_cvt_pk_bf16_f32 v109, v74, v75
	v_cvt_pk_bf16_f32 v110, v76, v77
	v_cvt_pk_bf16_f32 v111, v78, v79
	s_add_u32 s98, s40, s18
	s_addc_u32 s99, s41, 0
	s_add_i32 s25, s17, s4
	s_add_i32 m0, s25, 0xc000
	s_nop 0
	global_load_lds_dwordx4 v164, s[98:99]
	s_add_i32 m0, s25, 0xc400
	s_nop 0
	global_load_lds_dwordx4 v168, s[98:99]
	s_waitcnt lgkmcnt(0)
	s_barrier
	s_setprio 1
	v_mfma_f32_32x32x16_bf16 v[0:15], v[96:99], v[146:149], v[0:15]
	ds_read_b128 v[146:149], v229 offset:49152
	v_mfma_f32_32x32x16_bf16 v[0:15], v[100:103], v[150:153], v[0:15]
	ds_read_b128 v[150:153], v229 offset:57344
	v_mfma_f32_32x32x16_bf16 v[0:15], v[104:107], v[154:157], v[0:15]
	ds_read_b128 v[154:157], v230 offset:49152
	v_mfma_f32_32x32x16_bf16 v[0:15], v[108:111], v[158:161], v[0:15]
	ds_read_b128 v[158:161], v230 offset:57344
	v_mfma_f32_32x32x16_bf16 v[16:31], v[96:99], v[176:179], v[16:31]
	ds_read_b128 v[176:179], v232 offset:49152
	v_mfma_f32_32x32x16_bf16 v[16:31], v[100:103], v[180:183], v[16:31]
	ds_read_b128 v[180:183], v232 offset:57344
	v_mfma_f32_32x32x16_bf16 v[16:31], v[104:107], v[216:219], v[16:31]
	ds_read_b128 v[216:219], v238 offset:49152
	v_mfma_f32_32x32x16_bf16 v[16:31], v[108:111], v[220:223], v[16:31]
	ds_read_b128 v[220:223], v238 offset:57344
	v_mfma_f32_32x32x16_bf16 v[32:47], v[96:99], v[224:227], v[32:47]
	ds_read_b128 v[224:227], v203 offset:49152
	v_mfma_f32_32x32x16_bf16 v[32:47], v[100:103], v[234:237], v[32:47]
	ds_read_b128 v[234:237], v203 offset:57344
	v_mfma_f32_32x32x16_bf16 v[32:47], v[104:107], v[240:243], v[32:47]
	ds_read_b128 v[240:243], v205 offset:49152
	v_mfma_f32_32x32x16_bf16 v[32:47], v[108:111], v[244:247], v[32:47]
	ds_read_b128 v[244:247], v205 offset:57344
	v_mfma_f32_32x32x16_bf16 v[48:63], v[96:99], v[248:251], v[48:63]
	ds_read_b128 v[248:251], v214 offset:49152
	v_mfma_f32_32x32x16_bf16 v[48:63], v[100:103], v[196:199], v[48:63]
	ds_read_b128 v[196:199], v214 offset:57344
	v_mfma_f32_32x32x16_bf16 v[48:63], v[104:107], v[206:209], v[48:63]
	ds_read_b128 v[206:209], v175 offset:49152
	v_mfma_f32_32x32x16_bf16 v[48:63], v[108:111], v[210:213], v[48:63]
	ds_read_b128 v[210:213], v175 offset:57344
	s_setprio 0
	s_waitcnt vmcnt(0)
	s_barrier
	v_pk_add_f32 v[112:113], v[80:81], v[112:113]
	v_pk_add_f32 v[112:113], v[82:83], v[112:113]
	v_pk_add_f32 v[112:113], v[84:85], v[112:113]
	v_pk_add_f32 v[112:113], v[86:87], v[112:113]
	v_pk_add_f32 v[112:113], v[88:89], v[112:113]
	v_pk_add_f32 v[112:113], v[90:91], v[112:113]
	v_pk_add_f32 v[112:113], v[92:93], v[112:113]
	v_pk_add_f32 v[112:113], v[94:95], v[112:113]
	v_pk_add_f32 v[112:113], v[64:65], v[112:113]
	v_pk_add_f32 v[112:113], v[66:67], v[112:113]
	v_pk_add_f32 v[112:113], v[68:69], v[112:113]
	v_pk_add_f32 v[112:113], v[70:71], v[112:113]
	v_pk_add_f32 v[112:113], v[72:73], v[112:113]
	v_pk_add_f32 v[112:113], v[74:75], v[112:113]
	v_pk_add_f32 v[112:113], v[76:77], v[112:113]
	v_pk_add_f32 v[112:113], v[78:79], v[112:113]
	s_add_u32 s100, s42, s18
	s_addc_u32 s101, s43, 0
	s_add_i32 s18, s18, 0x4000
	s_and_b32 s18, s18, 0x1fffff
	s_add_u32 s98, s40, s18
	s_addc_u32 s99, s41, 0
	s_add_i32 s1, s24, s4
	s_add_i32 s25, s17, s4
	s_add_i32 m0, s1, 0xc000
	s_nop 0
	global_load_lds_dwordx4 v164, s[98:99]
	s_mov_b32 m0, s25
	s_nop 0
	global_load_lds_dwordx4 v166, s[100:101]
	s_add_i32 m0, s1, 0xc400
	s_nop 0
	global_load_lds_dwordx4 v168, s[98:99]
	s_add_i32 m0, s25, 0x400
	s_nop 0
	global_load_lds_dwordx4 v170, s[100:101]
	s_mov_b32 s1, s24
	s_mov_b32 s24, s0
	s_mov_b32 s0, s17
	s_mov_b32 s17, s1
	v_add_u32_e32 v215, s24, v195
	s_waitcnt lgkmcnt(0)
	s_barrier
; #define SBAR() __builtin_amdgcn_sched_barrier(0)
; #define NAM(P0, P1, t) do { if constexpr (NA) na_mask(P0, P1, kr_lo + (t), r0, qrow, qc, c0, hi, bl); } while (0)
; #define RESCN(a) do { if constexpr (NA) RESC(a); } while (0)
; template <int D0> __device__ __forceinline__ void pv_one(f32x16& od, int vb, bf16x8 pa0, bf16x8 pa1, bf16x8 pa2, bf16x8 pa3) {
;   const s16x4 l0 = tr_read<v_rd_off(D0, 0, 0)>(vb), h0 = tr_read<v_rd_off(D0, 0, 1)>(vb), l1 = tr_read<v_rd_off(D0, 1, 0)>(vb), h1 = tr_read<v_rd_off(D0, 1, 1)>(vb);
;   const s16x4 l2 = tr_read<v_rd_off(D0, 2, 0)>(vb), h2 = tr_read<v_rd_off(D0, 2, 1)>(vb), l3 = tr_read<v_rd_off(D0, 3, 0)>(vb), h3 = tr_read<v_rd_off(D0, 3, 1)>(vb);
;   asm volatile("s_waitcnt lgkmcnt(0)" ::: "memory"); SBAR();
;     ...
;   od = __builtin_amdgcn_mfma_f32_32x32x16_bf16(pa0, PK(l0, h0), od, 0, 0, 0);
;   od = __builtin_amdgcn_mfma_f32_32x32x16_bf16(pa1, PK(l1, h1), od, 0, 0, 0);
;   od = __builtin_amdgcn_mfma_f32_32x32x16_bf16(pa2, PK(l2, h2), od, 0, 0, 0);
;   od = __builtin_amdgcn_mfma_f32_32x32x16_bf16(pa3, PK(l3, h3), od, 0, 0, 0);
;     ...
; }
; __device__ __forceinline__ void pv_d0(f32x16* o, int vb, bf16x8 pa0, bf16x8 pa1, bf16x8 pa2, bf16x8 pa3) {
;   pv_one<0>(o[0], vb, pa0, pa1, pa2, pa3); pv_one<1>(o[1], vb, pa0, pa1, pa2, pa3); pv_one<2>(o[2], vb, pa0, pa1, pa2, pa3); pv_one<3>(o[3], vb, pa0, pa1, pa2, pa3);
; template <bool NA, int ROWB>
; __device__ __forceinline__ void attn_dma(const bf16* __restrict__ Qb, const bf16* __restrict__ Kh, const bf16* __restrict__ Vh, bf16* __restrict__ Ob, int NT, char* lds, const int tid, float* __restrict__ ssb, int qrow0, int kr_lo, const float* bl) {
;     ...
;   for (int t = 1; t + 1 < NT; t += 2) {
;     DMA_TILE(t + 1, bn);
;     SBAR(); qkt<false>(pB0, pB1, (const bf16*)(K_lds + bc * SHM_K), qr, nullptr, r32, hi); NAM(pB0, pB1, t);
;     finishSM(pA0, pA1, alA, l_reg, pa0, pa1, pa2, pa3); SBAR();
;     pv_d0(o, vb0 + bp * (int)SHM_V, pa0, pa1, pa2, pa3); PSM(pB0, pB1, mnB, alB); RESCN(alB);
;     VM0(); __syncthreads();
;     bp = bc; bc = bn; bn = NEXTB(bn);
;     if (t + 2 < NT) DMA_TILE(t + 2, bn);
;     SBAR(); qkt<false>(pA0, pA1, (const bf16*)(K_lds + bc * SHM_K), qr, nullptr, r32, hi); NAM(pA0, pA1, t + 1);
;     finishSM(pB0, pB1, alB, l_reg, pa0, pa1, pa2, pa3); SBAR();
;     pv_d0(o, vb0 + bp * (int)SHM_V, pa0, pa1, pa2, pa3); PSM(pA0, pA1, mnA, alA); RESCN(alA);
.Lgqa_loop:
	s_setprio 1
	v_mfma_f32_32x32x16_bf16 v[80:95], v[146:149], v[138:141], 0
	ds_read_b64_tr_b16 v[146:147], v215 offset:0
	ds_read_b64_tr_b16 v[148:149], v215 offset:2048
	v_mfma_f32_32x32x16_bf16 v[64:79], v[150:153], v[138:141], 0
	ds_read_b64_tr_b16 v[150:151], v215 offset:4096
	ds_read_b64_tr_b16 v[152:153], v215 offset:6144
	v_mfma_f32_32x32x16_bf16 v[80:95], v[154:157], v[142:145], v[80:95]
	ds_read_b64_tr_b16 v[154:155], v215 offset:8192
	ds_read_b64_tr_b16 v[156:157], v215 offset:10240
	v_mfma_f32_32x32x16_bf16 v[64:79], v[158:161], v[142:145], v[64:79]
	ds_read_b64_tr_b16 v[158:159], v215 offset:12288
	ds_read_b64_tr_b16 v[160:161], v215 offset:14336
	v_mfma_f32_32x32x16_bf16 v[80:95], v[176:179], v[134:137], v[80:95]
	ds_read_b64_tr_b16 v[176:177], v215 offset:512
	ds_read_b64_tr_b16 v[178:179], v215 offset:2560
	v_mfma_f32_32x32x16_bf16 v[64:79], v[180:183], v[134:137], v[64:79]
	ds_read_b64_tr_b16 v[180:181], v215 offset:4608
	ds_read_b64_tr_b16 v[182:183], v215 offset:6656
	v_mfma_f32_32x32x16_bf16 v[80:95], v[216:219], v[114:117], v[80:95]
	ds_read_b64_tr_b16 v[216:217], v215 offset:8704
	ds_read_b64_tr_b16 v[218:219], v215 offset:10752
	v_mfma_f32_32x32x16_bf16 v[64:79], v[220:223], v[114:117], v[64:79]
	ds_read_b64_tr_b16 v[220:221], v215 offset:12800
	ds_read_b64_tr_b16 v[222:223], v215 offset:14848
	v_mfma_f32_32x32x16_bf16 v[80:95], v[224:227], v[118:121], v[80:95]
	ds_read_b64_tr_b16 v[224:225], v215 offset:1024
	ds_read_b64_tr_b16 v[226:227], v215 offset:3072
	v_mfma_f32_32x32x16_bf16 v[64:79], v[234:237], v[118:121], v[64:79]
	ds_read_b64_tr_b16 v[234:235], v215 offset:5120
	ds_read_b64_tr_b16 v[236:237], v215 offset:7168
	v_mfma_f32_32x32x16_bf16 v[80:95], v[240:243], v[122:125], v[80:95]
	ds_read_b64_tr_b16 v[240:241], v215 offset:9216
	ds_read_b64_tr_b16 v[242:243], v215 offset:11264
	v_mfma_f32_32x32x16_bf16 v[64:79], v[244:247], v[122:125], v[64:79]
	ds_read_b64_tr_b16 v[244:245], v215 offset:13312
	ds_read_b64_tr_b16 v[246:247], v215 offset:15360
	v_mfma_f32_32x32x16_bf16 v[80:95], v[248:251], v[126:129], v[80:95]
	ds_read_b64_tr_b16 v[248:249], v215 offset:1536
	ds_read_b64_tr_b16 v[250:251], v215 offset:3584
	v_mfma_f32_32x32x16_bf16 v[64:79], v[196:199], v[126:129], v[64:79]
	ds_read_b64_tr_b16 v[196:197], v215 offset:5632
	ds_read_b64_tr_b16 v[198:199], v215 offset:7680
	v_mfma_f32_32x32x16_bf16 v[80:95], v[206:209], v[130:133], v[80:95]
	ds_read_b64_tr_b16 v[206:207], v215 offset:9728
	ds_read_b64_tr_b16 v[208:209], v215 offset:11776
	v_mfma_f32_32x32x16_bf16 v[64:79], v[210:213], v[130:133], v[64:79]
	ds_read_b64_tr_b16 v[210:211], v215 offset:13824
	ds_read_b64_tr_b16 v[212:213], v215 offset:15872
	s_setprio 0
	s_barrier
	s_nop 7
	v_exp_f32_e32 v80, v80
	v_exp_f32_e32 v81, v81
	v_exp_f32_e32 v82, v82
	v_exp_f32_e32 v83, v83
	v_exp_f32_e32 v84, v84
	v_exp_f32_e32 v85, v85
	v_exp_f32_e32 v86, v86
	v_exp_f32_e32 v87, v87
	v_exp_f32_e32 v88, v88
	v_exp_f32_e32 v89, v89
	v_exp_f32_e32 v90, v90
	v_exp_f32_e32 v91, v91
	v_exp_f32_e32 v92, v92
	v_exp_f32_e32 v93, v93
	v_exp_f32_e32 v94, v94
	v_exp_f32_e32 v95, v95
	v_add_u32_e32 v229, s0, v187
	v_add_u32_e32 v230, s0, v188
	v_add_u32_e32 v232, s0, v189
	v_add_u32_e32 v238, s0, v190
	v_add_u32_e32 v203, s0, v191
	v_add_u32_e32 v205, s0, v192
	v_add_u32_e32 v214, s0, v193
	v_add_u32_e32 v175, s0, v194
	v_exp_f32_e32 v64, v64
	v_exp_f32_e32 v65, v65
	v_exp_f32_e32 v66, v66
	v_exp_f32_e32 v67, v67
	v_exp_f32_e32 v68, v68
	v_exp_f32_e32 v69, v69
	v_exp_f32_e32 v70, v70
	v_exp_f32_e32 v71, v71
	v_exp_f32_e32 v72, v72
	v_exp_f32_e32 v73, v73
	v_exp_f32_e32 v74, v74
	v_exp_f32_e32 v75, v75
	v_exp_f32_e32 v76, v76
	v_exp_f32_e32 v77, v77
	v_exp_f32_e32 v78, v78
	v_exp_f32_e32 v79, v79
	v_cvt_pk_bf16_f32 v96, v80, v81
	v_cvt_pk_bf16_f32 v97, v82, v83
	v_cvt_pk_bf16_f32 v98, v84, v85
	v_cvt_pk_bf16_f32 v99, v86, v87
	v_cvt_pk_bf16_f32 v100, v88, v89
	v_cvt_pk_bf16_f32 v101, v90, v91
	v_cvt_pk_bf16_f32 v102, v92, v93
	v_cvt_pk_bf16_f32 v103, v94, v95
	v_cvt_pk_bf16_f32 v104, v64, v65
	v_cvt_pk_bf16_f32 v105, v66, v67
	v_cvt_pk_bf16_f32 v106, v68, v69
	v_cvt_pk_bf16_f32 v107, v70, v71
	v_cvt_pk_bf16_f32 v108, v72, v73
	v_cvt_pk_bf16_f32 v109, v74, v75
	v_cvt_pk_bf16_f32 v110, v76, v77
	v_cvt_pk_bf16_f32 v111, v78, v79
	s_waitcnt lgkmcnt(0)
	s_barrier
	s_setprio 1
	v_mfma_f32_32x32x16_bf16 v[0:15], v[96:99], v[146:149], v[0:15]
	ds_read_b128 v[146:149], v229 offset:49152
	v_mfma_f32_32x32x16_bf16 v[0:15], v[100:103], v[150:153], v[0:15]
	ds_read_b128 v[150:153], v229 offset:57344
	v_mfma_f32_32x32x16_bf16 v[0:15], v[104:107], v[154:157], v[0:15]
	ds_read_b128 v[154:157], v230 offset:49152
	v_mfma_f32_32x32x16_bf16 v[0:15], v[108:111], v[158:161], v[0:15]
	ds_read_b128 v[158:161], v230 offset:57344
	v_mfma_f32_32x32x16_bf16 v[16:31], v[96:99], v[176:179], v[16:31]
	ds_read_b128 v[176:179], v232 offset:49152
	v_mfma_f32_32x32x16_bf16 v[16:31], v[100:103], v[180:183], v[16:31]
	ds_read_b128 v[180:183], v232 offset:57344
	v_mfma_f32_32x32x16_bf16 v[16:31], v[104:107], v[216:219], v[16:31]
	ds_read_b128 v[216:219], v238 offset:49152
	v_mfma_f32_32x32x16_bf16 v[16:31], v[108:111], v[220:223], v[16:31]
	ds_read_b128 v[220:223], v238 offset:57344
	v_mfma_f32_32x32x16_bf16 v[32:47], v[96:99], v[224:227], v[32:47]
	ds_read_b128 v[224:227], v203 offset:49152
	v_mfma_f32_32x32x16_bf16 v[32:47], v[100:103], v[234:237], v[32:47]
	ds_read_b128 v[234:237], v203 offset:57344
	v_mfma_f32_32x32x16_bf16 v[32:47], v[104:107], v[240:243], v[32:47]
	ds_read_b128 v[240:243], v205 offset:49152
	v_mfma_f32_32x32x16_bf16 v[32:47], v[108:111], v[244:247], v[32:47]
	ds_read_b128 v[244:247], v205 offset:57344
	v_mfma_f32_32x32x16_bf16 v[48:63], v[96:99], v[248:251], v[48:63]
	ds_read_b128 v[248:251], v214 offset:49152
	v_mfma_f32_32x32x16_bf16 v[48:63], v[100:103], v[196:199], v[48:63]
	ds_read_b128 v[196:199], v214 offset:57344
	v_mfma_f32_32x32x16_bf16 v[48:63], v[104:107], v[206:209], v[48:63]
	ds_read_b128 v[206:209], v175 offset:49152
	v_mfma_f32_32x32x16_bf16 v[48:63], v[108:111], v[210:213], v[48:63]
	ds_read_b128 v[210:213], v175 offset:57344
	s_setprio 0
	s_waitcnt vmcnt(0)
	s_barrier
; #define SBAR() __builtin_amdgcn_sched_barrier(0)
; #define NAM(P0, P1, t) do { if constexpr (NA) na_mask(P0, P1, kr_lo + (t), r0, qrow, qc, c0, hi, bl); } while (0)
; #define PSM(P0, P1, MN, AL) do { if constexpr (NA) partialSM(P0, P1, m_reg, MN, AL); else { AL = 1.f; _Pragma("unroll") for (int r = 0; r < 16; ++r) P0[r] = __builtin_amdgcn_exp2f(P0[r]); } } while (0)
; #define RESCN(a) do { if constexpr (NA) RESC(a); } while (0)
; #define VM0() asm volatile("s_waitcnt vmcnt(0)" ::: "memory")
; #define NAM(P0, P1, t) do { if constexpr (NA) na_mask(P0, P1, kr_lo + (t), r0, qrow, qc, c0, hi, bl); } while (0)
; #define PSM(P0, P1, MN, AL) do { if constexpr (NA) partialSM(P0, P1, m_reg, MN, AL); else { AL = 1.f; _Pragma("unroll") for (int r = 0; r < 16; ++r) P0[r] = __builtin_amdgcn_exp2f(P0[r]); } } while (0)
; #define RESCN(a) do { if constexpr (NA) RESC(a); } while (0)
; template <bool NA, int ROWB>
; __device__ __forceinline__ void attn_dma(const bf16* __restrict__ Qb, const bf16* __restrict__ Kh, const bf16* __restrict__ Vh, bf16* __restrict__ Ob, int NT, char* lds, const int tid, float* __restrict__ ssb, int qrow0, int kr_lo, const float* bl) {
;     ...
;   for (int t = 1; t + 1 < NT; t += 2) {
;     DMA_TILE(t + 1, bn);
;     SBAR(); qkt<false>(pB0, pB1, (const bf16*)(K_lds + bc * SHM_K), qr, nullptr, r32, hi); NAM(pB0, pB1, t);
;     finishSM(pA0, pA1, alA, l_reg, pa0, pa1, pa2, pa3); SBAR();
;     pv_d0(o, vb0 + bp * (int)SHM_V, pa0, pa1, pa2, pa3); PSM(pB0, pB1, mnB, alB); RESCN(alB);
;     VM0(); __syncthreads();
;     bp = bc; bc = bn; bn = NEXTB(bn);
;     if (t + 2 < NT) DMA_TILE(t + 2, bn);
;     SBAR(); qkt<false>(pA0, pA1, (const bf16*)(K_lds + bc * SHM_K), qr, nullptr, r32, hi); NAM(pA0, pA1, t + 1);
;     finishSM(pB0, pB1, alB, l_reg, pa0, pa1, pa2, pa3); SBAR();
;     pv_d0(o, vb0 + bp * (int)SHM_V, pa0, pa1, pa2, pa3); PSM(pA0, pA1, mnA, alA); RESCN(alA);
;     VM0(); __syncthreads();
;     bp = bc; bc = bn; bn = NEXTB(bn);
;   }
;   SBAR(); qkt<false>(pB0, pB1, (const bf16*)(K_lds + bc * SHM_K), qr, nullptr, r32, hi); NAM(pB0, pB1, NT - 1);
;   finishSM(pA0, pA1, alA, l_reg, pa0, pa1, pa2, pa3); SBAR();
;   pv_d0(o, vb0 + bp * (int)SHM_V, pa0, pa1, pa2, pa3); PSM(pB0, pB1, mnB, alB); RESCN(alB);
;   finishSM(pB0, pB1, alB, l_reg, pa0, pa1, pa2, pa3); SBAR();
;   pv_d0(o, vb0 + bc * (int)SHM_V, pa0, pa1, pa2, pa3);
	v_pk_add_f32 v[112:113], v[80:81], v[112:113]
	v_pk_add_f32 v[112:113], v[82:83], v[112:113]
	v_pk_add_f32 v[112:113], v[84:85], v[112:113]
	v_pk_add_f32 v[112:113], v[86:87], v[112:113]
	v_pk_add_f32 v[112:113], v[88:89], v[112:113]
	v_pk_add_f32 v[112:113], v[90:91], v[112:113]
	v_pk_add_f32 v[112:113], v[92:93], v[112:113]
	v_pk_add_f32 v[112:113], v[94:95], v[112:113]
	v_pk_add_f32 v[112:113], v[64:65], v[112:113]
	v_pk_add_f32 v[112:113], v[66:67], v[112:113]
	v_pk_add_f32 v[112:113], v[68:69], v[112:113]
	v_pk_add_f32 v[112:113], v[70:71], v[112:113]
	v_pk_add_f32 v[112:113], v[72:73], v[112:113]
	v_pk_add_f32 v[112:113], v[74:75], v[112:113]
	v_pk_add_f32 v[112:113], v[76:77], v[112:113]
	v_pk_add_f32 v[112:113], v[78:79], v[112:113]
	s_add_u32 s100, s42, s18
	s_addc_u32 s101, s43, 0
	s_add_i32 s18, s18, 0x4000
	s_and_b32 s18, s18, 0x1fffff
	s_add_u32 s98, s40, s18
	s_addc_u32 s99, s41, 0
	s_add_i32 s1, s24, s4
	s_add_i32 s25, s17, s4
	s_add_i32 m0, s1, 0xc000
	s_nop 0
	global_load_lds_dwordx4 v164, s[98:99]
	s_mov_b32 m0, s25
	s_nop 0
	global_load_lds_dwordx4 v166, s[100:101]
	s_add_i32 m0, s1, 0xc400
	s_nop 0
	global_load_lds_dwordx4 v168, s[98:99]
	s_add_i32 m0, s25, 0x400
	s_nop 0
	global_load_lds_dwordx4 v170, s[100:101]
	s_mov_b32 s1, s24
	s_mov_b32 s24, s0
	s_mov_b32 s0, s17
	s_mov_b32 s17, s1
	v_add_u32_e32 v215, s24, v195
	s_waitcnt lgkmcnt(0)
	s_barrier
	s_add_i32 s16, s16, 1
	s_cmp_eq_u32 s16, 125
	s_cbranch_scc0 .Lgqa_loop
	s_setprio 1
	v_mfma_f32_32x32x16_bf16 v[80:95], v[146:149], v[138:141], 0
	v_mfma_f32_32x32x16_bf16 v[64:79], v[150:153], v[138:141], 0
	v_mfma_f32_32x32x16_bf16 v[80:95], v[154:157], v[142:145], v[80:95]
	v_mfma_f32_32x32x16_bf16 v[64:79], v[158:161], v[142:145], v[64:79]
	v_mfma_f32_32x32x16_bf16 v[80:95], v[176:179], v[134:137], v[80:95]
	v_mfma_f32_32x32x16_bf16 v[64:79], v[180:183], v[134:137], v[64:79]
	v_mfma_f32_32x32x16_bf16 v[80:95], v[216:219], v[114:117], v[80:95]
	v_mfma_f32_32x32x16_bf16 v[64:79], v[220:223], v[114:117], v[64:79]
	v_mfma_f32_32x32x16_bf16 v[80:95], v[224:227], v[118:121], v[80:95]
	v_mfma_f32_32x32x16_bf16 v[64:79], v[234:237], v[118:121], v[64:79]
	v_mfma_f32_32x32x16_bf16 v[80:95], v[240:243], v[122:125], v[80:95]
	v_mfma_f32_32x32x16_bf16 v[64:79], v[244:247], v[122:125], v[64:79]
	v_mfma_f32_32x32x16_bf16 v[80:95], v[248:251], v[126:129], v[80:95]
	v_mfma_f32_32x32x16_bf16 v[64:79], v[196:199], v[126:129], v[64:79]
	v_mfma_f32_32x32x16_bf16 v[80:95], v[206:209], v[130:133], v[80:95]
	v_mfma_f32_32x32x16_bf16 v[64:79], v[210:213], v[130:133], v[64:79]
	s_setprio 0
	s_waitcnt vmcnt(0)
	s_barrier
	s_cmp_ge_u32 s4, 0x2000
	s_cbranch_scc1 .Lgqa_trail
	s_barrier
.Lgqa_trail:
	s_nop 15
	v_exp_f32_e32 v212, v80
	v_exp_f32_e32 v214, v81
	v_exp_f32_e32 v210, v82
	v_exp_f32_e32 v213, v83
	v_exp_f32_e32 v208, v84
	v_exp_f32_e32 v211, v85
	v_exp_f32_e32 v207, v86
	v_exp_f32_e32 v209, v87
	v_exp_f32_e32 v203, v88
	v_exp_f32_e32 v206, v89
	v_exp_f32_e32 v198, v90
	v_exp_f32_e32 v205, v91
	v_exp_f32_e32 v196, v92
	v_exp_f32_e32 v199, v93
	v_exp_f32_e32 v175, v94
	v_exp_f32_e32 v197, v95
	v_exp_f32_e32 v64, v64
	v_exp_f32_e32 v65, v65
	v_exp_f32_e32 v66, v66
	v_exp_f32_e32 v67, v67
	v_exp_f32_e32 v68, v68
	v_exp_f32_e32 v69, v69
	v_exp_f32_e32 v70, v70
	v_exp_f32_e32 v71, v71
	v_exp_f32_e32 v72, v72
	v_exp_f32_e32 v73, v73
	v_exp_f32_e32 v74, v74
	v_exp_f32_e32 v75, v75
	v_exp_f32_e32 v76, v76
	v_exp_f32_e32 v77, v77
	v_exp_f32_e32 v78, v78
	v_exp_f32_e32 v79, v79
	v_add_f32_e32 v112, v112, v113
	v_mov_b32_e32 v113, 0
	v_mov_b32_e32 v228, v112
	s_nop 1
	v_permlane32_swap_b32_e32 v112, v228
	v_add_f32_e32 v112, v112, v228
	s_add_i32 s0, 0, 0x10000
	v_add_u32_e32 v84, s0, v187
	ds_read_b128 v[80:83], v84
	ds_read_b128 v[154:157], v84 offset:8192
	v_add_u32_e32 v100, s0, v188
	ds_read_b128 v[96:99], v100
	ds_read_b128 v[158:161], v100 offset:8192
	v_add_u32_e32 v100, s0, v189
	s_waitcnt lgkmcnt(3)
	v_mfma_f32_32x32x16_bf16 v[80:95], v[80:83], v[138:141], 0
	s_nop 0
	v_mov_b32_e32 v180, v66
	v_mov_b32_e32 v181, v67
	v_mov_b32_e32 v182, v68
	v_mov_b32_e32 v183, v69
	v_mov_b32_e32 v215, v70
	v_mov_b32_e32 v216, v71
	v_mov_b32_e32 v217, v72
	s_waitcnt lgkmcnt(1)
	v_mfma_f32_32x32x16_bf16 v[80:95], v[96:99], v[142:145], v[80:95]
	ds_read_b128 v[96:99], v100
	ds_read_b128 v[150:153], v100 offset:8192
	v_mov_b32_e32 v218, v73
	v_mov_b32_e32 v219, v74
	v_mov_b32_e32 v220, v75
	v_mov_b32_e32 v221, v76
	v_mov_b32_e32 v222, v77
	v_mov_b32_e32 v223, v78
	s_waitcnt lgkmcnt(1)
	v_mfma_f32_32x32x16_bf16 v[80:95], v[96:99], v[134:137], v[80:95]
	v_add_u32_e32 v96, s0, v190
	ds_read_b128 v[100:103], v96
	ds_read_b128 v[96:99], v96 offset:8192
	v_mov_b32_e32 v79, v79
	s_waitcnt lgkmcnt(1)
	v_mfma_f32_32x32x16_bf16 v[80:95], v[100:103], v[114:117], v[80:95]
	v_add_u32_e32 v100, s0, v191
	ds_read_b128 v[104:107], v100
	ds_read_b128 v[100:103], v100 offset:8192
	s_waitcnt lgkmcnt(1)
	v_mfma_f32_32x32x16_bf16 v[80:95], v[104:107], v[118:121], v[80:95]
	v_add_u32_e32 v104, s0, v192
	ds_read_b128 v[108:111], v104
	ds_read_b128 v[104:107], v104 offset:8192
	s_waitcnt lgkmcnt(1)
	v_mfma_f32_32x32x16_bf16 v[80:95], v[108:111], v[122:125], v[80:95]
	v_add_u32_e32 v108, s0, v193
	ds_read_b128 v[146:149], v108
	ds_read_b128 v[108:111], v108 offset:8192
	s_waitcnt lgkmcnt(1)
	v_mfma_f32_32x32x16_bf16 v[80:95], v[146:149], v[126:129], v[80:95]
	v_add_u32_e32 v146, s0, v194
	ds_read_b128 v[176:179], v146
	ds_read_b128 v[146:149], v146 offset:8192
	s_waitcnt lgkmcnt(1)
; #define SBAR() __builtin_amdgcn_sched_barrier(0)
; #define NAM(P0, P1, t) do { if constexpr (NA) na_mask(P0, P1, kr_lo + (t), r0, qrow, qc, c0, hi, bl); } while (0)
; #define PSM(P0, P1, MN, AL) do { if constexpr (NA) partialSM(P0, P1, m_reg, MN, AL); else { AL = 1.f; _Pragma("unroll") for (int r = 0; r < 16; ++r) P0[r] = __builtin_amdgcn_exp2f(P0[r]); } } while (0)
; #define RESCN(a) do { if constexpr (NA) RESC(a); } while (0)
; #define NAM(P0, P1, t) do { if constexpr (NA) na_mask(P0, P1, kr_lo + (t), r0, qrow, qc, c0, hi, bl); } while (0)
; #define PSM(P0, P1, MN, AL) do { if constexpr (NA) partialSM(P0, P1, m_reg, MN, AL); else { AL = 1.f; _Pragma("unroll") for (int r = 0; r < 16; ++r) P0[r] = __builtin_amdgcn_exp2f(P0[r]); } } while (0)
; #define RESCN(a) do { if constexpr (NA) RESC(a); } while (0)
; __device__ __forceinline__ void finishSM(f32x16& p0, f32x16& p1, float alpha, float& l_reg, bf16x8& pa0, bf16x8& pa1, bf16x8& pa2, bf16x8& pa3) {
;   for (int r = 0; r < 16; ++r) p1[r] = __builtin_amdgcn_exp2f(p1[r]);
;   float ps = 0; for (int r = 0; r < 16; ++r) ps += p0[r]; for (int r = 0; r < 16; ++r) ps += p1[r];
;   { auto rr = __builtin_amdgcn_permlane32_swap(__float_as_uint(ps), __float_as_uint(ps), false, false);
;     ps = __uint_as_float(rr[0]) + __uint_as_float(rr[1]); }
;   l_reg = l_reg * alpha + ps;
;     ...
;   PK4(p0, 0, pa0); PK4(p0, 8, pa1); PK4(p1, 0, pa2); PK4(p1, 8, pa3);
;     ...
; }
; template <bool NA, int ROWB>
; __device__ __forceinline__ void attn_dma(const bf16* __restrict__ Qb, const bf16* __restrict__ Kh, const bf16* __restrict__ Vh, bf16* __restrict__ Ob, int NT, char* lds, const int tid, float* __restrict__ ssb, int qrow0, int kr_lo, const float* bl) {
;     ...
;   SBAR(); qkt<false>(pB0, pB1, (const bf16*)(K_lds + bc * SHM_K), qr, nullptr, r32, hi); NAM(pB0, pB1, NT - 1);
;   finishSM(pA0, pA1, alA, l_reg, pa0, pa1, pa2, pa3); SBAR();
;   pv_d0(o, vb0 + bp * (int)SHM_V, pa0, pa1, pa2, pa3); PSM(pB0, pB1, mnB, alB); RESCN(alB);
;   finishSM(pB0, pB1, alB, l_reg, pa0, pa1, pa2, pa3); SBAR();
;   pv_d0(o, vb0 + bc * (int)SHM_V, pa0, pa1, pa2, pa3);
	v_mfma_f32_32x32x16_bf16 v[80:95], v[176:179], v[130:133], v[80:95]
	v_mov_b32_e32 v177, v64
	v_add_f32_e32 v64, 0, v212
	v_add_f32_e32 v64, v214, v64
	v_add_f32_e32 v64, v210, v64
	v_add_f32_e32 v64, v213, v64
	v_add_f32_e32 v64, v208, v64
	v_add_f32_e32 v64, v211, v64
	v_add_f32_e32 v64, v207, v64
	v_add_f32_e32 v64, v209, v64
	v_add_f32_e32 v64, v203, v64
	v_add_f32_e32 v64, v206, v64
	v_add_f32_e32 v64, v198, v64
	v_add_f32_e32 v64, v205, v64
	v_add_f32_e32 v64, v196, v64
	v_mov_b32_e32 v179, v65
	v_add_f32_e32 v64, v199, v64
	v_add_f32_e32 v64, v175, v64
	v_add_f32_e32 v64, v197, v64
	v_add_f32_e32 v64, v64, v177
	v_add_f32_e32 v64, v179, v64
	v_add_f32_e32 v64, v180, v64
	v_add_f32_e32 v64, v181, v64
	v_add_f32_e32 v64, v182, v64
	v_add_f32_e32 v64, v183, v64
	v_add_f32_e32 v64, v215, v64
	v_add_f32_e32 v64, v216, v64
	v_add_f32_e32 v64, v217, v64
	v_add_f32_e32 v64, v218, v64
	v_add_f32_e32 v64, v219, v64
	v_add_f32_e32 v64, v220, v64
	v_add_f32_e32 v64, v221, v64
	v_add_f32_e32 v64, v222, v64
	v_add_f32_e32 v64, v223, v64
	v_add_f32_e32 v176, v79, v64
	v_mov_b32_e32 v178, v176
	s_nop 1
	v_permlane32_swap_b32_e32 v176, v178
	v_cvt_pk_bf16_f32 v64, v212, v214
	v_cvt_pk_bf16_f32 v65, v210, v213
	v_cvt_pk_bf16_f32 v66, v208, v211
	v_cvt_pk_bf16_f32 v67, v207, v209
	v_cvt_pk_bf16_f32 v68, v203, v206
	v_cvt_pk_bf16_f32 v69, v198, v205
	v_cvt_pk_bf16_f32 v70, v196, v199
	v_cvt_pk_bf16_f32 v71, v175, v197
	v_cvt_pk_bf16_f32 v72, v177, v179
	v_cvt_pk_bf16_f32 v73, v180, v181
	v_cvt_pk_bf16_f32 v74, v182, v183
	v_cvt_pk_bf16_f32 v75, v215, v216
	v_cvt_pk_bf16_f32 v76, v217, v218
	v_cvt_pk_bf16_f32 v77, v219, v220
	v_cvt_pk_bf16_f32 v78, v221, v222
	v_cvt_pk_bf16_f32 v79, v223, v79
	s_nop 0
	ds_read_b64_tr_b16 v[180:181], v195 offset:0
	ds_read_b64_tr_b16 v[182:183], v195 offset:0x800
	ds_read_b64_tr_b16 v[196:197], v195 offset:0x1000
	ds_read_b64_tr_b16 v[198:199], v195 offset:0x1800
	ds_read_b64_tr_b16 v[206:207], v195 offset:0x2000
	ds_read_b64_tr_b16 v[208:209], v195 offset:0x2800
	ds_read_b64_tr_b16 v[210:211], v195 offset:0x3000
	ds_read_b64_tr_b16 v[212:213], v195 offset:0x3800
	s_waitcnt lgkmcnt(0)
	s_nop 0
	v_mfma_f32_32x32x16_bf16 v[0:15], v[64:67], v[180:183], v[0:15]
	ds_read_b64_tr_b16 v[180:181], v195 offset:0x200
	ds_read_b64_tr_b16 v[182:183], v195 offset:0xa00
	v_mfma_f32_32x32x16_bf16 v[0:15], v[68:71], v[196:199], v[0:15]
	ds_read_b64_tr_b16 v[196:197], v195 offset:0x1200
	ds_read_b64_tr_b16 v[198:199], v195 offset:0x1a00
	v_mfma_f32_32x32x16_bf16 v[0:15], v[72:75], v[206:209], v[0:15]
	ds_read_b64_tr_b16 v[206:207], v195 offset:0x2200
	ds_read_b64_tr_b16 v[208:209], v195 offset:0x2a00
	v_mfma_f32_32x32x16_bf16 v[0:15], v[76:79], v[210:213], v[0:15]
	ds_read_b64_tr_b16 v[210:211], v195 offset:0x3200
	ds_read_b64_tr_b16 v[212:213], v195 offset:0x3a00
	s_waitcnt lgkmcnt(0)
	v_mfma_f32_32x32x16_bf16 v[16:31], v[64:67], v[180:183], v[16:31]
	ds_read_b64_tr_b16 v[180:181], v195 offset:0x400
	ds_read_b64_tr_b16 v[182:183], v195 offset:0xc00
	v_mfma_f32_32x32x16_bf16 v[16:31], v[68:71], v[196:199], v[16:31]
	ds_read_b64_tr_b16 v[196:197], v195 offset:0x1400
	ds_read_b64_tr_b16 v[198:199], v195 offset:0x1c00
	v_mfma_f32_32x32x16_bf16 v[16:31], v[72:75], v[206:209], v[16:31]
	ds_read_b64_tr_b16 v[206:207], v195 offset:0x2400
	ds_read_b64_tr_b16 v[208:209], v195 offset:0x2c00
	v_mfma_f32_32x32x16_bf16 v[16:31], v[76:79], v[210:213], v[16:31]
	ds_read_b64_tr_b16 v[210:211], v195 offset:0x3400
	ds_read_b64_tr_b16 v[212:213], v195 offset:0x3c00
	s_waitcnt lgkmcnt(0)
	v_mfma_f32_32x32x16_bf16 v[32:47], v[64:67], v[180:183], v[32:47]
	ds_read_b64_tr_b16 v[180:181], v195 offset:0x600
	ds_read_b64_tr_b16 v[182:183], v195 offset:0xe00
	v_mfma_f32_32x32x16_bf16 v[32:47], v[68:71], v[196:199], v[32:47]
	ds_read_b64_tr_b16 v[196:197], v195 offset:0x1600
	ds_read_b64_tr_b16 v[198:199], v195 offset:0x1e00
	v_mfma_f32_32x32x16_bf16 v[32:47], v[72:75], v[206:209], v[32:47]
	ds_read_b64_tr_b16 v[206:207], v195 offset:0x2600
	ds_read_b64_tr_b16 v[208:209], v195 offset:0x2e00
	v_mfma_f32_32x32x16_bf16 v[32:47], v[76:79], v[210:213], v[32:47]
	ds_read_b64_tr_b16 v[210:211], v195 offset:0x3600
	ds_read_b64_tr_b16 v[212:213], v195 offset:0x3e00
	s_waitcnt lgkmcnt(0)
	v_mfma_f32_32x32x16_bf16 v[48:63], v[64:67], v[180:183], v[48:63]
	v_exp_f32_e32 v175, v80
	v_exp_f32_e32 v180, v81
	v_exp_f32_e32 v181, v82
	v_exp_f32_e32 v182, v83
	v_exp_f32_e32 v183, v84
	v_exp_f32_e32 v80, v90
	v_exp_f32_e32 v86, v86
	v_mfma_f32_32x32x16_bf16 v[48:63], v[68:71], v[196:199], v[48:63]
	v_exp_f32_e32 v196, v85
	v_exp_f32_e32 v87, v87
	v_exp_f32_e32 v88, v88
	v_exp_f32_e32 v89, v89
	v_exp_f32_e32 v81, v91
	v_exp_f32_e32 v82, v92
	v_exp_f32_e32 v83, v93
	v_mfma_f32_32x32x16_bf16 v[48:63], v[72:75], v[206:209], v[48:63]
	v_exp_f32_e32 v84, v94
	v_exp_f32_e32 v85, v95
	v_mfma_f32_32x32x16_bf16 v[48:63], v[76:79], v[210:213], v[48:63]
	v_mfma_f32_32x32x16_bf16 v[64:79], v[154:157], v[138:141], 0
	v_mfma_f32_32x32x16_bf16 v[64:79], v[158:161], v[142:145], v[64:79]
	v_mfma_f32_32x32x16_bf16 v[64:79], v[150:153], v[134:137], v[64:79]
	v_mfma_f32_32x32x16_bf16 v[64:79], v[96:99], v[114:117], v[64:79]
	v_mfma_f32_32x32x16_bf16 v[64:79], v[100:103], v[118:121], v[64:79]
	v_mfma_f32_32x32x16_bf16 v[64:79], v[104:107], v[122:125], v[64:79]
	v_mfma_f32_32x32x16_bf16 v[64:79], v[108:111], v[126:129], v[64:79]
	s_waitcnt lgkmcnt(0)
; #define SBAR() __builtin_amdgcn_sched_barrier(0)
; __device__ __forceinline__ int crow(int r, int hi) { return (r & 3) + 8 * (r >> 2) + 4 * hi; }
; template <bool NA, int ROWB>
; __device__ __forceinline__ void attn_dma(const bf16* __restrict__ Qb, const bf16* __restrict__ Kh, const bf16* __restrict__ Vh, bf16* __restrict__ Ob, int NT, char* lds, const int tid, float* __restrict__ ssb, int qrow0, int kr_lo, const float* bl) {
;     ...
;   finishSM(pB0, pB1, alB, l_reg, pa0, pa1, pa2, pa3); SBAR();
;   pv_d0(o, vb0 + bc * (int)SHM_V, pa0, pa1, pa2, pa3);
;   if (hi == 0) li_l[r32] = l_reg; asm volatile("s_waitcnt lgkmcnt(0)" ::: "memory");
;   float rli[16];
; #pragma unroll
;   for (int r = 0; r < 16; ++r) rli[r] = __builtin_amdgcn_rcpf(li_l[crow(r, hi)]);
	v_mfma_f32_32x32x16_bf16 v[64:79], v[146:149], v[130:133], v[64:79]
	s_nop 11
	v_exp_f32_e32 v90, v64
	v_add_f32_e32 v64, 0, v175
	v_add_f32_e32 v64, v180, v64
	v_add_f32_e32 v64, v181, v64
	v_add_f32_e32 v64, v182, v64
	v_add_f32_e32 v64, v183, v64
	v_add_f32_e32 v64, v196, v64
	v_add_f32_e32 v64, v86, v64
	v_add_f32_e32 v64, v87, v64
	v_add_f32_e32 v64, v88, v64
	v_add_f32_e32 v64, v89, v64
	v_add_f32_e32 v64, v80, v64
	v_add_f32_e32 v64, v81, v64
	v_add_f32_e32 v64, v82, v64
	v_exp_f32_e32 v91, v65
	v_add_f32_e32 v64, v83, v64
	v_exp_f32_e32 v92, v66
	v_add_f32_e32 v64, v84, v64
	v_exp_f32_e32 v93, v67
	v_add_f32_e32 v64, v85, v64
	v_exp_f32_e32 v94, v68
	v_add_f32_e32 v64, v64, v90
	v_exp_f32_e32 v95, v69
	v_add_f32_e32 v64, v91, v64
	v_exp_f32_e32 v96, v70
	v_add_f32_e32 v64, v92, v64
	v_exp_f32_e32 v97, v71
	v_add_f32_e32 v64, v93, v64
	v_exp_f32_e32 v98, v72
	v_add_f32_e32 v64, v94, v64
	v_exp_f32_e32 v99, v73
	v_add_f32_e32 v64, v95, v64
	v_exp_f32_e32 v100, v74
	v_add_f32_e32 v64, v96, v64
	v_exp_f32_e32 v101, v75
	v_add_f32_e32 v64, v97, v64
	v_exp_f32_e32 v102, v76
	v_add_f32_e32 v64, v98, v64
	v_exp_f32_e32 v103, v77
	v_add_f32_e32 v64, v99, v64
	v_exp_f32_e32 v104, v78
	v_add_f32_e32 v64, v100, v64
	v_exp_f32_e32 v79, v79
	v_add_f32_e32 v64, v101, v64
	v_add_f32_e32 v64, v102, v64
	v_add_f32_e32 v64, v103, v64
	v_add_f32_e32 v64, v104, v64
	v_add_f32_e32 v177, v79, v64
	v_mov_b32_e32 v179, v177
	s_nop 1
	v_permlane32_swap_b32_e32 v177, v179
	v_cvt_pk_bf16_f32 v64, v175, v180
	v_cvt_pk_bf16_f32 v65, v181, v182
	v_cvt_pk_bf16_f32 v66, v183, v196
	v_cvt_pk_bf16_f32 v67, v86, v87
	v_cvt_pk_bf16_f32 v68, v88, v89
	v_cvt_pk_bf16_f32 v69, v80, v81
	v_cvt_pk_bf16_f32 v70, v82, v83
	v_cvt_pk_bf16_f32 v71, v84, v85
	v_cvt_pk_bf16_f32 v72, v90, v91
	v_cvt_pk_bf16_f32 v73, v92, v93
	v_cvt_pk_bf16_f32 v74, v94, v95
	v_cvt_pk_bf16_f32 v75, v96, v97
	v_cvt_pk_bf16_f32 v76, v98, v99
	v_cvt_pk_bf16_f32 v77, v100, v101
	v_cvt_pk_bf16_f32 v78, v102, v103
	v_cvt_pk_bf16_f32 v79, v104, v79
	s_nop 0
	ds_read_b64_tr_b16 v[80:81], v201 offset:0
	ds_read_b64_tr_b16 v[82:83], v201 offset:0x800
	ds_read_b64_tr_b16 v[84:85], v201 offset:0x1000
	ds_read_b64_tr_b16 v[86:87], v201 offset:0x1800
	ds_read_b64_tr_b16 v[88:89], v201 offset:0x2000
	ds_read_b64_tr_b16 v[90:91], v201 offset:0x2800
	ds_read_b64_tr_b16 v[92:93], v201 offset:0x3000
	ds_read_b64_tr_b16 v[94:95], v201 offset:0x3800
	s_waitcnt lgkmcnt(0)
	s_nop 0
	v_mfma_f32_32x32x16_bf16 v[0:15], v[64:67], v[80:83], v[0:15]
	ds_read_b64_tr_b16 v[80:81], v201 offset:0x200
	ds_read_b64_tr_b16 v[82:83], v201 offset:0xa00
	v_mfma_f32_32x32x16_bf16 v[0:15], v[68:71], v[84:87], v[0:15]
	ds_read_b64_tr_b16 v[84:85], v201 offset:0x1200
	ds_read_b64_tr_b16 v[86:87], v201 offset:0x1a00
	v_mfma_f32_32x32x16_bf16 v[0:15], v[72:75], v[88:91], v[0:15]
	ds_read_b64_tr_b16 v[88:89], v201 offset:0x2200
	ds_read_b64_tr_b16 v[90:91], v201 offset:0x2a00
	v_mfma_f32_32x32x16_bf16 v[0:15], v[76:79], v[92:95], v[0:15]
	ds_read_b64_tr_b16 v[92:93], v201 offset:0x3200
	ds_read_b64_tr_b16 v[94:95], v201 offset:0x3a00
	s_waitcnt lgkmcnt(0)
	v_mfma_f32_32x32x16_bf16 v[16:31], v[64:67], v[80:83], v[16:31]
	ds_read_b64_tr_b16 v[80:81], v201 offset:0x400
	ds_read_b64_tr_b16 v[82:83], v201 offset:0xc00
	v_mfma_f32_32x32x16_bf16 v[16:31], v[68:71], v[84:87], v[16:31]
	ds_read_b64_tr_b16 v[84:85], v201 offset:0x1400
	ds_read_b64_tr_b16 v[86:87], v201 offset:0x1c00
	v_mfma_f32_32x32x16_bf16 v[16:31], v[72:75], v[88:91], v[16:31]
	ds_read_b64_tr_b16 v[88:89], v201 offset:0x2400
	ds_read_b64_tr_b16 v[90:91], v201 offset:0x2c00
	v_mfma_f32_32x32x16_bf16 v[16:31], v[76:79], v[92:95], v[16:31]
	ds_read_b64_tr_b16 v[92:93], v201 offset:0x3400
	ds_read_b64_tr_b16 v[94:95], v201 offset:0x3c00
	s_waitcnt lgkmcnt(0)
	v_mfma_f32_32x32x16_bf16 v[32:47], v[64:67], v[80:83], v[32:47]
	ds_read_b64_tr_b16 v[80:81], v201 offset:0x600
	ds_read_b64_tr_b16 v[82:83], v201 offset:0xe00
	v_mfma_f32_32x32x16_bf16 v[32:47], v[68:71], v[84:87], v[32:47]
	ds_read_b64_tr_b16 v[84:85], v201 offset:0x1600
	ds_read_b64_tr_b16 v[86:87], v201 offset:0x1e00
	v_mfma_f32_32x32x16_bf16 v[32:47], v[72:75], v[88:91], v[32:47]
	ds_read_b64_tr_b16 v[88:89], v201 offset:0x2600
	ds_read_b64_tr_b16 v[90:91], v201 offset:0x2e00
	v_mfma_f32_32x32x16_bf16 v[32:47], v[76:79], v[92:95], v[32:47]
	ds_read_b64_tr_b16 v[92:93], v201 offset:0x3600
	ds_read_b64_tr_b16 v[94:95], v201 offset:0x3e00
	s_waitcnt lgkmcnt(0)
	v_mfma_f32_32x32x16_bf16 v[48:63], v[64:67], v[80:83], v[48:63]
	v_mfma_f32_32x32x16_bf16 v[48:63], v[68:71], v[84:87], v[48:63]
	v_mfma_f32_32x32x16_bf16 v[48:63], v[72:75], v[88:91], v[48:63]
	v_mfma_f32_32x32x16_bf16 v[48:63], v[76:79], v[92:95], v[48:63]
	s_and_saveexec_b64 s[4:5], vcc
	v_pk_add_f32 v[64:65], v[176:177], v[178:179]
	s_nop 0
	v_add_f32_e32 v64, v112, v64
	v_add_f32_e32 v64, v64, v65
	ds_write_b32 v204, v64
	s_or_b64 exec, exec, s[4:5]
	s_lshl_b64 s[0:1], s[6:7], 12
	v_readlane_b32 s4, v254, 41
	s_waitcnt lgkmcnt(0)
	v_add_u32_e32 v72, v185, v186
	s_add_u32 s4, s4, s0
	v_readlane_b32 s0, v254, 42
	ds_read_b128 v[64:67], v72
	ds_read_b128 v[68:71], v72 offset:32
	s_addc_u32 s5, s0, s1
	s_lshl_b64 s[0:1], s[6:7], 6
	v_readlane_b32 s6, v254, 32
	v_readlane_b32 s7, v254, 33
	s_add_u32 s6, s6, s0
	s_addc_u32 s7, s7, s1
	s_lshl_b32 s0, s15, 1
	s_add_u32 s0, s4, s0
	s_waitcnt lgkmcnt(1)
	v_rcp_f32_e32 v84, v64
	s_addc_u32 s1, s5, 0
	v_mov_b32_e32 v74, v200
	v_rcp_f32_e32 v85, v65
	v_rcp_f32_e32 v86, v66
	v_rcp_f32_e32 v87, v67
	s_waitcnt lgkmcnt(0)
; __device__ __forceinline__ float xs(float v, int o, int lane) { return __int_as_float(__builtin_amdgcn_ds_bpermute((lane ^ o) << 2, __float_as_int(v))); }
; __device__ __forceinline__ void st16_wt(void* p, u32x4 v) { asm volatile("global_store_dwordx4 %0, %1, off sc0 sc1\n\ts_nop 1" :: "v"(p), "v"(v) : "memory"); }
; template <bool NA, int ROWB>
; __device__ __forceinline__ void attn_dma(const bf16* __restrict__ Qb, const bf16* __restrict__ Kh, const bf16* __restrict__ Vh, bf16* __restrict__ Ob, int NT, char* lds, const int tid, float* __restrict__ ssb, int qrow0, int kr_lo, const float* bl) {
;     ...
;   int tid_e = tid; asm volatile("" : "+v"(tid_e));
;   const int lane_e = tid_e & 63, wid_e = tid_e >> 6, r32_e = lane_e & 31, hi_e = lane_e >> 5;
;   char* sg = lds + 100 * 1024 + wid_e * 4096;
; #pragma unroll
;   for (int half = 0; half < 2; ++half) {
;     char* wb_e = sg + hi_e * 1024 + r32_e * 2 + hi_e * 64;
;     char* wb_o = sg + hi_e * 1024 + r32_e * 2 - hi_e * 64;
; #pragma unroll
;     for (int rr = 0; rr < 8; ++rr) { const int r = half * 8 + rr; const int rc = ((rr & 3) + 8 * (rr >> 2)) * 256;
; #pragma unroll
;       for (int d0 = 0; d0 < 4; ++d0) { const float v = o[d0][r] * rli[r]; *(bf16*)(((d0 & 1) ? wb_o : wb_e) + rc + d0 * 64) = (bf16)(cvtpk(v, v) & 0xffffu); } }
;     asm volatile("s_waitcnt lgkmcnt(0)" ::: "memory");
;     const char* rb_e = sg + (lane_e >> 4) * 256 + (lane_e & 15) * 16;
;     const char* rb_o = sg + (lane_e >> 4) * 256 + (((lane_e & 15) * 16) ^ 64);
;     bf16* gb = Ow + (long)(half * 16 + (lane_e >> 4)) * LDO + (lane_e & 15) * 8;
; #pragma unroll
;     for (int i = 0; i < 4; ++i) { const u32x4 w = *(const u32x4*)(((i & 1) ? rb_o : rb_e) + i * 1024); st16_wt(gb + (long)i * 4 * LDO, w);
;       float q = sumsq8(w); q += xs(q, 1, lane_e); q += xs(q, 2, lane_e); q += xs(q, 4, lane_e); q += xs(q, 8, lane_e);
;       if ((lane_e & 15) == 0) ssb[(size_t)(wid_e * QBLK + half * 16 + (lane_e >> 4) + 4 * i) * 16] = q; }
	v_rcp_f32_e32 v88, v68
	v_rcp_f32_e32 v89, v69
	v_rcp_f32_e32 v90, v70
	v_rcp_f32_e32 v91, v71
	ds_read_b128 v[68:71], v72 offset:64
	ds_read_b128 v[64:67], v72 offset:96
	v_lshl_add_u64 v[72:73], s[0:1], 0, v[172:173]
	v_readlane_b32 s0, v254, 20
	v_ashrrev_i32_e32 v78, 6, v74
	v_bfe_u32 v76, v74, 5, 1
	v_lshlrev_b32_e32 v80, 1, v74
	v_and_b32_e32 v93, 15, v74
	v_and_b32_e32 v75, 63, v74
	v_lshl_add_u32 v77, v78, 12, s0
	v_lshlrev_b32_e32 v79, 10, v76
	v_and_b32_e32 v80, 62, v80
	v_lshlrev_b32_e32 v112, 4, v93
	v_add3_u32 v79, v77, v79, v80
	v_lshlrev_b32_e32 v80, 6, v76
	v_bfe_u32 v92, v74, 4, 2
	v_lshl_add_u64 v[82:83], v[72:73], 0, v[112:113]
	v_lshlrev_b32_e32 v72, 2, v75
	v_mul_f32_e32 v0, v0, v84
	v_lshl_add_u32 v81, v92, 8, v77
	v_xor_b32_e32 v77, 4, v72
	v_xor_b32_e32 v76, 8, v72
	v_xor_b32_e32 v75, 16, v72
	v_xor_b32_e32 v74, 32, v72
	v_lshl_or_b32 v72, v78, 5, v92
	v_cvt_pk_bf16_f32 v0, v0, v0
	v_add_u32_e32 v78, v79, v80
	ds_write_b16 v78, v0
	v_mul_f32_e32 v0, v16, v84
	v_cvt_pk_bf16_f32 v0, v0, v0
	v_sub_u32_e32 v16, v79, v80
	ds_write_b16 v16, v0 offset:64
	v_mul_f32_e32 v0, v32, v84
	v_cvt_pk_bf16_f32 v0, v0, v0
	ds_write_b16 v78, v0 offset:128
	v_mul_f32_e32 v0, v48, v84
	v_cvt_pk_bf16_f32 v0, v0, v0
	ds_write_b16 v16, v0 offset:192
	v_mul_f32_e32 v0, v1, v85
	v_cvt_pk_bf16_f32 v0, v0, v0
	ds_write_b16 v78, v0 offset:256
	v_mul_f32_e32 v0, v17, v85
	v_cvt_pk_bf16_f32 v0, v0, v0
	ds_write_b16 v16, v0 offset:320
	v_mul_f32_e32 v0, v33, v85
	v_cvt_pk_bf16_f32 v0, v0, v0
	ds_write_b16 v78, v0 offset:384
	v_mul_f32_e32 v0, v49, v85
	v_cvt_pk_bf16_f32 v0, v0, v0
	ds_write_b16 v16, v0 offset:448
	v_mul_f32_e32 v0, v2, v86
	v_cvt_pk_bf16_f32 v0, v0, v0
	ds_write_b16 v78, v0 offset:512
	v_mul_f32_e32 v0, v18, v86
	v_cvt_pk_bf16_f32 v0, v0, v0
	ds_write_b16 v16, v0 offset:576
	v_mul_f32_e32 v0, v34, v86
	v_cvt_pk_bf16_f32 v0, v0, v0
	ds_write_b16 v78, v0 offset:640
	v_mul_f32_e32 v0, v50, v86
	v_cvt_pk_bf16_f32 v0, v0, v0
	ds_write_b16 v16, v0 offset:704
	v_mul_f32_e32 v0, v3, v87
	v_cvt_pk_bf16_f32 v0, v0, v0
	ds_write_b16 v78, v0 offset:768
	v_mul_f32_e32 v0, v19, v87
	v_cvt_pk_bf16_f32 v0, v0, v0
	ds_write_b16 v16, v0 offset:832
	v_mul_f32_e32 v0, v35, v87
	v_cvt_pk_bf16_f32 v0, v0, v0
	ds_write_b16 v78, v0 offset:896
	v_mul_f32_e32 v0, v51, v87
	v_cvt_pk_bf16_f32 v0, v0, v0
	ds_write_b16 v16, v0 offset:960
	v_mul_f32_e32 v0, v4, v88
	v_cvt_pk_bf16_f32 v0, v0, v0
	ds_write_b16 v78, v0 offset:2048
	v_mul_f32_e32 v0, v20, v88
	v_cvt_pk_bf16_f32 v0, v0, v0
	ds_write_b16 v16, v0 offset:2112
	v_mul_f32_e32 v0, v36, v88
	v_cvt_pk_bf16_f32 v0, v0, v0
	ds_write_b16 v78, v0 offset:2176
	v_mul_f32_e32 v0, v52, v88
	v_cvt_pk_bf16_f32 v0, v0, v0
	ds_write_b16 v16, v0 offset:2240
	v_mul_f32_e32 v0, v5, v89
	v_cvt_pk_bf16_f32 v0, v0, v0
	ds_write_b16 v78, v0 offset:2304
	v_mul_f32_e32 v0, v21, v89
	v_cvt_pk_bf16_f32 v0, v0, v0
	ds_write_b16 v16, v0 offset:2368
	v_mul_f32_e32 v0, v37, v89
	v_cvt_pk_bf16_f32 v0, v0, v0
	ds_write_b16 v78, v0 offset:2432
	v_mul_f32_e32 v0, v53, v89
	v_cvt_pk_bf16_f32 v0, v0, v0
	ds_write_b16 v16, v0 offset:2496
	v_mul_f32_e32 v0, v6, v90
	v_cvt_pk_bf16_f32 v0, v0, v0
	ds_write_b16 v78, v0 offset:2560
	v_mul_f32_e32 v0, v22, v90
	v_cvt_pk_bf16_f32 v0, v0, v0
	ds_write_b16 v16, v0 offset:2624
	v_mul_f32_e32 v0, v38, v90
	v_cvt_pk_bf16_f32 v0, v0, v0
	ds_write_b16 v78, v0 offset:2688
	v_mul_f32_e32 v0, v54, v90
	v_cvt_pk_bf16_f32 v0, v0, v0
	ds_write_b16 v16, v0 offset:2752
	v_mul_f32_e32 v0, v7, v91
	v_cvt_pk_bf16_f32 v0, v0, v0
	ds_write_b16 v78, v0 offset:2816
	v_mul_f32_e32 v0, v23, v91
	v_cvt_pk_bf16_f32 v0, v0, v0
	ds_write_b16 v16, v0 offset:2880
	v_mul_f32_e32 v0, v39, v91
	v_cvt_pk_bf16_f32 v0, v0, v0
	ds_write_b16 v78, v0 offset:2944
	v_mul_f32_e32 v0, v55, v91
	v_cvt_pk_bf16_f32 v0, v0, v0
	ds_write_b16 v16, v0 offset:3008
	s_waitcnt lgkmcnt(0)
	v_add_u32_e32 v2, v81, v112
	ds_read_b128 v[4:7], v2
	v_lshlrev_b32_e32 v0, 12, v92
	v_mov_b32_e32 v1, v113
	v_lshl_add_u64 v[0:1], v[82:83], 0, v[0:1]
	s_mov_b64 s[0:1], 0x800
	v_lshl_add_u64 v[0:1], v[0:1], 0, s[0:1]
	s_waitcnt lgkmcnt(0)
	global_store_dwordx4 v[0:1], v[4:7], off sc0 sc1
	s_nop 1
	v_lshlrev_b32_e32 v3, 16, v4
	v_and_b32_e32 v4, 0xffff0000, v4
	v_mul_f32_e32 v4, v4, v4
	v_fmac_f32_e32 v4, v3, v3
	v_lshlrev_b32_e32 v3, 16, v5
	v_and_b32_e32 v5, 0xffff0000, v5
	v_mul_f32_e32 v5, v5, v5
	v_fmac_f32_e32 v5, v3, v3
	v_add_f32_e32 v3, v4, v5
	v_and_b32_e32 v5, 0xffff0000, v6
	v_lshlrev_b32_e32 v4, 16, v6
	v_mul_f32_e32 v5, v5, v5
	v_fmac_f32_e32 v5, v4, v4
	v_add_f32_e32 v3, v5, v3
	v_and_b32_e32 v5, 0xffff0000, v7
	v_lshlrev_b32_e32 v4, 16, v7
	v_mul_f32_e32 v5, v5, v5
	v_fmac_f32_e32 v5, v4, v4
	v_add_f32_e32 v3, v5, v3
	s_nop 1
	v_mov_b32_dpp v4, v3 quad_perm:[1,0,3,2] row_mask:0xf bank_mask:0xf
	s_lshl_b32 s4, s14, 2
	s_add_u32 s4, s6, s4
	s_addc_u32 s5, s7, 0
	s_add_u32 s6, s4, 0x25cc0020
	s_waitcnt lgkmcnt(0)
	v_add_f32_e32 v3, v3, v4
	s_nop 1
	v_mov_b32_dpp v4, v3 quad_perm:[2,3,0,1] row_mask:0xf bank_mask:0xf
	s_addc_u32 s7, s5, 0
	v_cmp_eq_u32_e64 s[4:5], 0, v93
	s_waitcnt lgkmcnt(0)
	v_add_f32_e32 v3, v3, v4
	s_nop 1
	v_mov_b32_dpp v4, v3 row_half_mirror row_mask:0xf bank_mask:0xf
	s_waitcnt lgkmcnt(0)
	v_add_f32_e32 v3, v3, v4
	s_nop 1
	v_mov_b32_dpp v4, v3 row_mirror row_mask:0xf bank_mask:0xf
	s_and_saveexec_b64 s[14:15], s[4:5]
	v_readlane_b32 s16, v254, 47
	v_readlane_b32 s28, v254, 34
	s_mov_b32 s36, s38
	v_readlane_b32 s17, v254, 48
	v_readlane_b32 s29, v254, 35
	s_cbranch_execz .LBB0_111
	v_ashrrev_i32_e32 v73, 31, v72
	v_lshlrev_b64 v[6:7], 6, v[72:73]
	v_lshl_add_u64 v[6:7], s[6:7], 0, v[6:7]
	s_waitcnt lgkmcnt(0)
	v_add_f32_e32 v3, v3, v4
	global_store_dword v[6:7], v3, off
